# v12 without the chain write-through/wbl2 change: null-gain wait removal, ResProb and P5 epilogue/mid batching, in-loop LDS-DMA SGPR-base form (subset), slot-handoff trimming in all 17 K-loops
# speedup vs baseline: 1.0015x; 1.0015x over previous
.LBB0_1649:
	s_waitcnt vmcnt(15)
	v_lshlrev_b32_e32 v246, 16, v134
	v_and_b32_e32 v247, 0xffff0000, v134
	v_pk_mul_f32 v[130:131], v[130:131], v[246:247]
	v_lshlrev_b32_e32 v246, 16, v135
	v_and_b32_e32 v247, 0xffff0000, v135
	v_pk_mul_f32 v[132:133], v[132:133], v[246:247]
	v_lshlrev_b32_e32 v246, 16, v136
	v_and_b32_e32 v247, 0xffff0000, v136
	v_pk_mul_f32 v[126:127], v[126:127], v[246:247]
	v_lshlrev_b32_e32 v246, 16, v137
	v_and_b32_e32 v247, 0xffff0000, v137
	v_pk_mul_f32 v[128:129], v[128:129], v[246:247]
	v_cvt_pk_bf16_f32 v134, v130, v131
	v_cvt_pk_bf16_f32 v135, v132, v133
	v_cvt_pk_bf16_f32 v136, v126, v127
	v_cvt_pk_bf16_f32 v137, v128, v129
	global_store_dwordx4 v245, v[134:137], s[18:19]
	s_waitcnt vmcnt(15)
	v_lshlrev_b32_e32 v246, 16, v138
	v_and_b32_e32 v247, 0xffff0000, v138
	v_pk_mul_f32 v[122:123], v[122:123], v[246:247]
	v_lshlrev_b32_e32 v246, 16, v139
	v_and_b32_e32 v247, 0xffff0000, v139
	v_pk_mul_f32 v[124:125], v[124:125], v[246:247]
	v_lshlrev_b32_e32 v246, 16, v140
	v_and_b32_e32 v247, 0xffff0000, v140
	v_pk_mul_f32 v[118:119], v[118:119], v[246:247]
	v_lshlrev_b32_e32 v246, 16, v141
	v_and_b32_e32 v247, 0xffff0000, v141
	v_pk_mul_f32 v[120:121], v[120:121], v[246:247]
	v_cvt_pk_bf16_f32 v138, v122, v123
	v_cvt_pk_bf16_f32 v139, v124, v125
	v_cvt_pk_bf16_f32 v140, v118, v119
	v_cvt_pk_bf16_f32 v141, v120, v121
	global_store_dwordx4 v245, v[138:141], s[18:19] offset:256
	s_add_u32 vcc_lo, s18, 0x20000
	s_addc_u32 vcc_hi, s19, 0
	s_waitcnt vmcnt(15)
	v_lshlrev_b32_e32 v246, 16, v142
	v_and_b32_e32 v247, 0xffff0000, v142
	v_pk_mul_f32 v[114:115], v[114:115], v[246:247]
	v_lshlrev_b32_e32 v246, 16, v143
	v_and_b32_e32 v247, 0xffff0000, v143
	v_pk_mul_f32 v[116:117], v[116:117], v[246:247]
	v_lshlrev_b32_e32 v246, 16, v144
	v_and_b32_e32 v247, 0xffff0000, v144
	v_pk_mul_f32 v[110:111], v[110:111], v[246:247]
	v_lshlrev_b32_e32 v246, 16, v145
	v_and_b32_e32 v247, 0xffff0000, v145
	v_pk_mul_f32 v[112:113], v[112:113], v[246:247]
	v_cvt_pk_bf16_f32 v142, v114, v115
	v_cvt_pk_bf16_f32 v143, v116, v117
	v_cvt_pk_bf16_f32 v144, v110, v111
	v_cvt_pk_bf16_f32 v145, v112, v113
	global_store_dwordx4 v245, v[142:145], vcc
	s_waitcnt vmcnt(15)
	v_lshlrev_b32_e32 v246, 16, v146
	v_and_b32_e32 v247, 0xffff0000, v146
	v_pk_mul_f32 v[106:107], v[106:107], v[246:247]
	v_lshlrev_b32_e32 v246, 16, v147
	v_and_b32_e32 v247, 0xffff0000, v147
	v_pk_mul_f32 v[108:109], v[108:109], v[246:247]
	v_lshlrev_b32_e32 v246, 16, v148
	v_and_b32_e32 v247, 0xffff0000, v148
	v_pk_mul_f32 v[102:103], v[102:103], v[246:247]
	v_lshlrev_b32_e32 v246, 16, v149
	v_and_b32_e32 v247, 0xffff0000, v149
	v_pk_mul_f32 v[104:105], v[104:105], v[246:247]
	v_cvt_pk_bf16_f32 v146, v106, v107
	v_cvt_pk_bf16_f32 v147, v108, v109
	v_cvt_pk_bf16_f32 v148, v102, v103
	v_cvt_pk_bf16_f32 v149, v104, v105
	global_store_dwordx4 v245, v[146:149], vcc offset:256
	s_add_u32 vcc_lo, s18, 0x40000
	s_addc_u32 vcc_hi, s19, 0
	s_waitcnt vmcnt(15)
	v_lshlrev_b32_e32 v246, 16, v150
	v_and_b32_e32 v247, 0xffff0000, v150
	v_pk_mul_f32 v[98:99], v[98:99], v[246:247]
	v_lshlrev_b32_e32 v246, 16, v151
	v_and_b32_e32 v247, 0xffff0000, v151
	v_pk_mul_f32 v[100:101], v[100:101], v[246:247]
	v_lshlrev_b32_e32 v246, 16, v152
	v_and_b32_e32 v247, 0xffff0000, v152
	v_pk_mul_f32 v[94:95], v[94:95], v[246:247]
	v_lshlrev_b32_e32 v246, 16, v153
	v_and_b32_e32 v247, 0xffff0000, v153
	v_pk_mul_f32 v[96:97], v[96:97], v[246:247]
	v_cvt_pk_bf16_f32 v150, v98, v99
	v_cvt_pk_bf16_f32 v151, v100, v101
	v_cvt_pk_bf16_f32 v152, v94, v95
	v_cvt_pk_bf16_f32 v153, v96, v97
	global_store_dwordx4 v245, v[150:153], vcc
	s_waitcnt vmcnt(15)
	v_lshlrev_b32_e32 v246, 16, v154
	v_and_b32_e32 v247, 0xffff0000, v154
	v_pk_mul_f32 v[90:91], v[90:91], v[246:247]
	v_lshlrev_b32_e32 v246, 16, v155
	v_and_b32_e32 v247, 0xffff0000, v155
	v_pk_mul_f32 v[92:93], v[92:93], v[246:247]
	v_lshlrev_b32_e32 v246, 16, v156
	v_and_b32_e32 v247, 0xffff0000, v156
	v_pk_mul_f32 v[86:87], v[86:87], v[246:247]
	v_lshlrev_b32_e32 v246, 16, v157
	v_and_b32_e32 v247, 0xffff0000, v157
	v_pk_mul_f32 v[88:89], v[88:89], v[246:247]
	v_cvt_pk_bf16_f32 v154, v90, v91
	v_cvt_pk_bf16_f32 v155, v92, v93
	v_cvt_pk_bf16_f32 v156, v86, v87
	v_cvt_pk_bf16_f32 v157, v88, v89
	global_store_dwordx4 v245, v[154:157], vcc offset:256
	s_add_u32 vcc_lo, s18, 0x60000
	s_addc_u32 vcc_hi, s19, 0
	s_waitcnt vmcnt(15)
	v_lshlrev_b32_e32 v246, 16, v158
	v_and_b32_e32 v247, 0xffff0000, v158
	v_pk_mul_f32 v[82:83], v[82:83], v[246:247]
	v_lshlrev_b32_e32 v246, 16, v159
	v_and_b32_e32 v247, 0xffff0000, v159
	v_pk_mul_f32 v[84:85], v[84:85], v[246:247]
	v_lshlrev_b32_e32 v246, 16, v160
	v_and_b32_e32 v247, 0xffff0000, v160
	v_pk_mul_f32 v[78:79], v[78:79], v[246:247]
	v_lshlrev_b32_e32 v246, 16, v161
	v_and_b32_e32 v247, 0xffff0000, v161
	v_pk_mul_f32 v[80:81], v[80:81], v[246:247]
	v_cvt_pk_bf16_f32 v158, v82, v83
	v_cvt_pk_bf16_f32 v159, v84, v85
	v_cvt_pk_bf16_f32 v160, v78, v79
	v_cvt_pk_bf16_f32 v161, v80, v81
	global_store_dwordx4 v245, v[158:161], vcc
	s_waitcnt vmcnt(15)
	v_lshlrev_b32_e32 v246, 16, v188
	v_and_b32_e32 v247, 0xffff0000, v188
	v_pk_mul_f32 v[74:75], v[74:75], v[246:247]
	v_lshlrev_b32_e32 v246, 16, v189
	v_and_b32_e32 v247, 0xffff0000, v189
	v_pk_mul_f32 v[76:77], v[76:77], v[246:247]
	v_lshlrev_b32_e32 v246, 16, v190
	v_and_b32_e32 v247, 0xffff0000, v190
	v_pk_mul_f32 v[70:71], v[70:71], v[246:247]
	v_lshlrev_b32_e32 v246, 16, v191
	v_and_b32_e32 v247, 0xffff0000, v191
	v_pk_mul_f32 v[72:73], v[72:73], v[246:247]
	v_cvt_pk_bf16_f32 v188, v74, v75
	v_cvt_pk_bf16_f32 v189, v76, v77
	v_cvt_pk_bf16_f32 v190, v70, v71
	v_cvt_pk_bf16_f32 v191, v72, v73
	global_store_dwordx4 v245, v[188:191], vcc offset:256
	s_add_u32 vcc_lo, s18, 0x100000
	s_addc_u32 vcc_hi, s19, 0
	s_waitcnt vmcnt(15)
	v_lshlrev_b32_e32 v246, 16, v192
	v_and_b32_e32 v247, 0xffff0000, v192
	v_pk_mul_f32 v[66:67], v[66:67], v[246:247]
	v_lshlrev_b32_e32 v246, 16, v193
	v_and_b32_e32 v247, 0xffff0000, v193
	v_pk_mul_f32 v[68:69], v[68:69], v[246:247]
	v_lshlrev_b32_e32 v246, 16, v194
	v_and_b32_e32 v247, 0xffff0000, v194
	v_pk_mul_f32 v[62:63], v[62:63], v[246:247]
	v_lshlrev_b32_e32 v246, 16, v195
	v_and_b32_e32 v247, 0xffff0000, v195
	v_pk_mul_f32 v[64:65], v[64:65], v[246:247]
	v_cvt_pk_bf16_f32 v192, v66, v67
	v_cvt_pk_bf16_f32 v193, v68, v69
	v_cvt_pk_bf16_f32 v194, v62, v63
	v_cvt_pk_bf16_f32 v195, v64, v65
	global_store_dwordx4 v245, v[192:195], vcc
	s_waitcnt vmcnt(15)
	v_lshlrev_b32_e32 v246, 16, v196
	v_and_b32_e32 v247, 0xffff0000, v196
	v_pk_mul_f32 v[58:59], v[58:59], v[246:247]
	v_lshlrev_b32_e32 v246, 16, v197
	v_and_b32_e32 v247, 0xffff0000, v197
	v_pk_mul_f32 v[60:61], v[60:61], v[246:247]
	v_lshlrev_b32_e32 v246, 16, v198
	v_and_b32_e32 v247, 0xffff0000, v198
	v_pk_mul_f32 v[54:55], v[54:55], v[246:247]
	v_lshlrev_b32_e32 v246, 16, v199
	v_and_b32_e32 v247, 0xffff0000, v199
	v_pk_mul_f32 v[56:57], v[56:57], v[246:247]
	v_cvt_pk_bf16_f32 v196, v58, v59
	v_cvt_pk_bf16_f32 v197, v60, v61
	v_cvt_pk_bf16_f32 v198, v54, v55
	v_cvt_pk_bf16_f32 v199, v56, v57
	global_store_dwordx4 v245, v[196:199], vcc offset:256
	s_add_u32 vcc_lo, s18, 0x120000
	s_addc_u32 vcc_hi, s19, 0
	s_waitcnt vmcnt(15)
	v_lshlrev_b32_e32 v246, 16, v200
	v_and_b32_e32 v247, 0xffff0000, v200
	v_pk_mul_f32 v[50:51], v[50:51], v[246:247]
	v_lshlrev_b32_e32 v246, 16, v201
	v_and_b32_e32 v247, 0xffff0000, v201
	v_pk_mul_f32 v[52:53], v[52:53], v[246:247]
	v_lshlrev_b32_e32 v246, 16, v202
	v_and_b32_e32 v247, 0xffff0000, v202
	v_pk_mul_f32 v[46:47], v[46:47], v[246:247]
	v_lshlrev_b32_e32 v246, 16, v203
	v_and_b32_e32 v247, 0xffff0000, v203
	v_pk_mul_f32 v[48:49], v[48:49], v[246:247]
	v_cvt_pk_bf16_f32 v200, v50, v51
	v_cvt_pk_bf16_f32 v201, v52, v53
	v_cvt_pk_bf16_f32 v202, v46, v47
	v_cvt_pk_bf16_f32 v203, v48, v49
	global_store_dwordx4 v245, v[200:203], vcc
	s_waitcnt vmcnt(15)
	v_lshlrev_b32_e32 v246, 16, v204
	v_and_b32_e32 v247, 0xffff0000, v204
	v_pk_mul_f32 v[42:43], v[42:43], v[246:247]
	v_lshlrev_b32_e32 v246, 16, v205
	v_and_b32_e32 v247, 0xffff0000, v205
	v_pk_mul_f32 v[44:45], v[44:45], v[246:247]
	v_lshlrev_b32_e32 v246, 16, v206
	v_and_b32_e32 v247, 0xffff0000, v206
	v_pk_mul_f32 v[38:39], v[38:39], v[246:247]
	v_lshlrev_b32_e32 v246, 16, v207
	v_and_b32_e32 v247, 0xffff0000, v207
	v_pk_mul_f32 v[40:41], v[40:41], v[246:247]
	v_cvt_pk_bf16_f32 v204, v42, v43
	v_cvt_pk_bf16_f32 v205, v44, v45
	v_cvt_pk_bf16_f32 v206, v38, v39
	v_cvt_pk_bf16_f32 v207, v40, v41
	global_store_dwordx4 v245, v[204:207], vcc offset:256
	s_add_u32 vcc_lo, s18, 0x140000
	s_addc_u32 vcc_hi, s19, 0
	s_waitcnt vmcnt(15)
	v_lshlrev_b32_e32 v246, 16, v208
	v_and_b32_e32 v247, 0xffff0000, v208
	v_pk_mul_f32 v[34:35], v[34:35], v[246:247]
	v_lshlrev_b32_e32 v246, 16, v209
	v_and_b32_e32 v247, 0xffff0000, v209
	v_pk_mul_f32 v[36:37], v[36:37], v[246:247]
	v_lshlrev_b32_e32 v246, 16, v210
	v_and_b32_e32 v247, 0xffff0000, v210
	v_pk_mul_f32 v[30:31], v[30:31], v[246:247]
	v_lshlrev_b32_e32 v246, 16, v211
	v_and_b32_e32 v247, 0xffff0000, v211
	v_pk_mul_f32 v[32:33], v[32:33], v[246:247]
	v_cvt_pk_bf16_f32 v208, v34, v35
	v_cvt_pk_bf16_f32 v209, v36, v37
	v_cvt_pk_bf16_f32 v210, v30, v31
	v_cvt_pk_bf16_f32 v211, v32, v33
	global_store_dwordx4 v245, v[208:211], vcc
	s_waitcnt vmcnt(15)
	v_lshlrev_b32_e32 v246, 16, v212
	v_and_b32_e32 v247, 0xffff0000, v212
	v_pk_mul_f32 v[26:27], v[26:27], v[246:247]
	v_lshlrev_b32_e32 v246, 16, v213
	v_and_b32_e32 v247, 0xffff0000, v213
	v_pk_mul_f32 v[28:29], v[28:29], v[246:247]
	v_lshlrev_b32_e32 v246, 16, v214
	v_and_b32_e32 v247, 0xffff0000, v214
	v_pk_mul_f32 v[22:23], v[22:23], v[246:247]
	v_lshlrev_b32_e32 v246, 16, v215
	v_and_b32_e32 v247, 0xffff0000, v215
	v_pk_mul_f32 v[24:25], v[24:25], v[246:247]
	v_cvt_pk_bf16_f32 v212, v26, v27
	v_cvt_pk_bf16_f32 v213, v28, v29
	v_cvt_pk_bf16_f32 v214, v22, v23
	v_cvt_pk_bf16_f32 v215, v24, v25
	global_store_dwordx4 v245, v[212:215], vcc offset:256
	s_add_u32 vcc_lo, s18, 0x160000
	s_addc_u32 vcc_hi, s19, 0
	s_waitcnt vmcnt(15)
	v_lshlrev_b32_e32 v246, 16, v216
	v_and_b32_e32 v247, 0xffff0000, v216
	v_pk_mul_f32 v[18:19], v[18:19], v[246:247]
	v_lshlrev_b32_e32 v246, 16, v217
	v_and_b32_e32 v247, 0xffff0000, v217
	v_pk_mul_f32 v[20:21], v[20:21], v[246:247]
	v_lshlrev_b32_e32 v246, 16, v218
	v_and_b32_e32 v247, 0xffff0000, v218
	v_pk_mul_f32 v[14:15], v[14:15], v[246:247]
	v_lshlrev_b32_e32 v246, 16, v219
	v_and_b32_e32 v247, 0xffff0000, v219
	v_pk_mul_f32 v[16:17], v[16:17], v[246:247]
	v_cvt_pk_bf16_f32 v216, v18, v19
	v_cvt_pk_bf16_f32 v217, v20, v21
	v_cvt_pk_bf16_f32 v218, v14, v15
	v_cvt_pk_bf16_f32 v219, v16, v17
	global_store_dwordx4 v245, v[216:219], vcc
	s_waitcnt vmcnt(15)
	v_lshlrev_b32_e32 v246, 16, v220
	v_and_b32_e32 v247, 0xffff0000, v220
	v_pk_mul_f32 v[10:11], v[10:11], v[246:247]
	v_lshlrev_b32_e32 v246, 16, v221
	v_and_b32_e32 v247, 0xffff0000, v221
	v_pk_mul_f32 v[12:13], v[12:13], v[246:247]
	v_lshlrev_b32_e32 v246, 16, v222
	v_and_b32_e32 v247, 0xffff0000, v222
	v_pk_mul_f32 v[6:7], v[6:7], v[246:247]
	v_lshlrev_b32_e32 v246, 16, v223
	v_and_b32_e32 v247, 0xffff0000, v223
	v_pk_mul_f32 v[8:9], v[8:9], v[246:247]
	v_cvt_pk_bf16_f32 v220, v10, v11
	v_cvt_pk_bf16_f32 v221, v12, v13
	v_cvt_pk_bf16_f32 v222, v6, v7
	v_cvt_pk_bf16_f32 v223, v8, v9
	global_store_dwordx4 v245, v[220:223], vcc offset:256
	s_and_b64 vcc, exec, s[6:7]
	s_mov_b64 s[6:7], -1
	s_cbranch_vccnz .LBB0_1634
	s_andn2_b64 vcc, exec, s[12:13]
	s_cbranch_vccnz .LBB0_1633
	s_barrier
	s_branch .LBB0_1633
